# attention phase: one static s_setprio 1 for waves 4-7 at P2 entry, reset at P2 exit
# baseline (speedup 1.0000x reference)
; #define LAS3 __attribute__((address_space(3)))
; __device__ __forceinline__ unsigned cvtpk(float lo, float hi) { f32x2_t v = {lo, hi}; bf16x2_t b = __builtin_convertvector(v, bf16x2_t); return __builtin_bit_cast(unsigned, b); }
; #define ATT_WAIT_BAR() asm volatile("s_waitcnt vmcnt(0) lgkmcnt(0)\n\ts_barrier" ::: "memory")
; #define LAS __attribute__((address_space(3)))
; __device__ __forceinline__ void fox_unit(int b, int hh, int qb, const bf16_t* Q, const bf16_t* __restrict__ K, const bf16_t* __restrict__ V, bf16_t* O, ...
;     ...
;     LAS3 unsigned char* stg = shm + L_OST + wid * OSTW;
; #pragma unroll
;     for (int g = 0; g < 4; ++g) {
;         u32x2 w0; w0.x = cvtpk(o0[4 * g], o0[4 * g + 1]); w0.y = cvtpk(o0[4 * g + 2], o0[4 * g + 3]);
;         u32x2 w1; w1.x = cvtpk(o1[4 * g], o1[4 * g + 1]); w1.y = cvtpk(o1[4 * g + 2], o1[4 * g + 3]);
;         *(LAS3 u32x2*)(stg + r32 * 144 + g * 16 + hi * 8) = w0;
;         *(LAS3 u32x2*)(stg + r32 * 144 + 64 + g * 16 + hi * 8) = w1;
;     }
;     asm volatile("s_waitcnt lgkmcnt(0)" ::: "memory");
;     bf16_t* Ow = O + (rowbase + qw0) * DM + hh * 64;
; #pragma unroll
;     for (int i = 0; i < 4; ++i) { const int row = i * 8 + (lane >> 3), ch = lane & 7; const u32x4 v = *(const LAS3 u32x4*)(stg + row * 144 + ch * 16); *(u32x4*)(Ow + (long)row * DM + ch * 8) = v; }
;     ATT_WAIT_BAR();
; __global__ void __launch_bounds__(NWAVES * 64, 2) fwd_megakernel(Args args) {
;     ...
;         volatile LAS unsigned* qw = (volatile LAS unsigned*)(lds + att::L_FLAG + 64);
;         for (;;) {
;             if (tid == 0) qw[0] = atomicAdd(CTL, 1u);
;             __syncthreads();
;             const unsigned idx = qw[0];
.LBB0_355:
	v_writelane_b32 v249, s74, 25
	s_nop 1
	v_writelane_b32 v249, s75, 26
	v_writelane_b32 v249, s90, 27
	v_writelane_b32 v249, s59, 28
	v_writelane_b32 v249, s88, 29
	s_nop 1
	v_writelane_b32 v249, s89, 30
	v_writelane_b32 v249, s68, 31
	s_nop 1
	v_writelane_b32 v249, s69, 32
	v_writelane_b32 v249, s70, 33
	v_writelane_b32 v249, s71, 34
	v_writelane_b32 v249, s64, 35
	s_nop 1
	v_writelane_b32 v249, s65, 36
	v_writelane_b32 v249, s62, 37
	s_nop 1
	v_writelane_b32 v249, s63, 38
	v_writelane_b32 v249, s60, 39
	s_nop 1
	v_writelane_b32 v249, s61, 40
	s_or_b64 exec, exec, s[0:1]
	s_add_u32 s0, s66, 0x1c00000
	s_addc_u32 s1, s67, 0
	s_add_u32 s88, s66, 0xb000000
	s_addc_u32 s95, s67, 0
	v_writelane_b32 v249, s0, 41
	s_add_u32 s96, s66, 0xf000000
	s_addc_u32 s97, s67, 0
	v_writelane_b32 v249, s1, 42
	s_add_u32 s93, s66, 0x13000000
	v_writelane_b32 v249, s66, 43
	v_cmp_eq_u32_e64 s[0:1], 0, v180
	s_addc_u32 s94, s67, 0
	v_writelane_b32 v249, s67, 44
	v_writelane_b32 v249, s0, 45
	v_lshlrev_b32_e32 v7, 1, v178
	v_and_b32_e32 v8, 0xc0, v130
	v_writelane_b32 v249, s1, 46
	v_cmp_ne_u32_e64 s[0:1], 0, v180
	v_and_b32_e32 v4, 24, v181
	v_and_b32_e32 v7, 32, v7
	v_writelane_b32 v249, s0, 47
	v_lshl_or_b32 v8, v185, 8, v8
	v_or3_b32 v8, v8, v7, v4
	v_writelane_b32 v249, s1, 48
	s_add_i32 s1, 0, 0x10c00
	v_writelane_b32 v249, s1, 49
	s_add_i32 s1, 0, 0x10800
	v_writelane_b32 v249, s1, 50
	s_add_i32 s1, 0, 0x1f004
	v_writelane_b32 v249, s1, 51
	s_add_i32 s1, 0, 0x1f008
	s_add_i32 s0, 0, 0x1f040
	v_writelane_b32 v249, s1, 52
	v_add_u32_e32 v139, 0, v8
	v_lshlrev_b32_e32 v8, 2, v185
	v_lshrrev_b32_e32 v9, 2, v178
	v_writelane_b32 v249, s0, 53
	v_and_or_b32 v9, v9, 3, v8
	v_writelane_b32 v249, s93, 54
	v_add_u32_e32 v7, 0, v7
	v_lshlrev_b32_e32 v9, 6, v9
	v_writelane_b32 v249, s94, 55
	v_lshlrev_b32_e32 v5, 10, v185
	v_lshlrev_b32_e32 v6, 4, v182
	v_add3_u32 v165, v7, v4, v9
	v_mov_b32_e32 v7, 0x3f80
	v_cmp_gt_u32_e64 s[8:9], 32, v180
	v_writelane_b32 v249, s88, 56
	s_waitcnt lgkmcnt(0)
	v_lshlrev_b32_e32 v2, 10, v180
	v_mov_b32_e32 v3, 0
	v_add3_u32 v137, 0, v5, v6
	v_lshlrev_b32_e32 v140, 10, v183
	s_add_i32 s92, 0, 0x10000
	v_cndmask_b32_e64 v115, 0, v7, s[8:9]
	v_mov_b32_e32 v7, 0x3f803f80
	v_sub_u32_e32 v167, v8, v182
	v_or_b32_e32 v5, v5, v6
	v_writelane_b32 v249, s95, 57
	v_lshrrev_b32_e32 v135, 2, v180
	v_lshlrev_b32_e32 v134, 10, v182
	v_lshlrev_b32_e32 v136, 3, v185
	s_mov_b32 s81, 0
	v_mul_u32_u24_e32 v162, 0x90, v182
	v_lshlrev_b32_e32 v163, 4, v184
	v_lshlrev_b32_e32 v138, 3, v184
	v_mul_u32_u24_e32 v164, 0x90, v183
	v_mov_b32_e32 v141, v3
	v_or_b32_e32 v142, 0x2000, v140
	v_mov_b32_e32 v143, v3
	v_or_b32_e32 v144, 0x4000, v140
	v_mov_b32_e32 v145, v3
	v_or_b32_e32 v146, 0x6000, v140
	v_mov_b32_e32 v147, v3
	v_lshlrev_b32_e32 v148, 11, v180
	v_mov_b32_e32 v149, v3
	v_lshlrev_b32_e32 v150, 7, v180
	v_mov_b32_e32 v151, v3
	v_add_u32_e32 v166, s92, v6
	s_mov_b32 s76, 0x3f803f80
	v_cndmask_b32_e64 v114, 0, v7, s[8:9]
	v_mov_b32_e32 v116, v3
	v_mov_b32_e32 v117, v3
	v_add_u32_e32 v168, 0xffffe100, v167
	v_add_u32_e32 v169, 0, v5
	v_add_u32_e32 v170, 0xffffe0c0, v167
	v_add_u32_e32 v171, 0xffffe080, v167
	v_lshlrev_b32_e32 v152, 1, v2
	v_mov_b32_e32 v172, 0x260
	s_add_i32 s89, 0, 0x1f00c
	s_add_i32 s90, 0, 0x1f014
	s_add_i32 s91, 0, 0x1f018
	s_add_i32 s4, 0, 0x1f01c
	v_mov_b32_e32 v173, s0
	v_lshlrev_b32_e32 v154, 1, v4
	v_mov_b32_e32 v174, 0xff800000
	v_writelane_b32 v249, s96, 58
	s_barrier
	v_writelane_b32 v249, s97, 59
	v_lshrrev_b32_e32 v186, 8, v178
	s_nop 0
	v_readfirstlane_b32 s98, v186
	s_cmp_eq_u32 s98, 0
	s_cbranch_scc1 .Lp2_prio_skip
	s_setprio 1
.Lp2_prio_skip:
	s_branch .LBB0_359
.LBB0_356:
	s_or_b64 exec, exec, s[0:1]
	v_readlane_b32 s0, v249, 61
	s_mulk_i32 s0, 0x1200
	s_add_i32 s0, s0, 0
	s_add_i32 s2, s0, 0x11400
	v_add3_u32 v2, s2, v162, v136
	v_cvt_pk_bf16_f32 v6, v6, v7
	v_cvt_pk_bf16_f32 v7, v14, v15
	v_cvt_pk_bf16_f32 v4, v4, v5
	v_cvt_pk_bf16_f32 v5, v10, v11
	v_cvt_pk_bf16_f32 v10, v12, v13
	v_cvt_pk_bf16_f32 v11, v22, v23
	v_cvt_pk_bf16_f32 v8, v8, v9
	v_cvt_pk_bf16_f32 v9, v20, v21
	v_readlane_b32 s0, v249, 63
	ds_write2_b64 v2, v[6:7], v[10:11] offset1:2
	ds_write2_b64 v2, v[4:5], v[8:9] offset0:8 offset1:10
	v_cvt_pk_bf16_f32 v4, v18, v19
	v_cvt_pk_bf16_f32 v5, v34, v35
	v_cvt_pk_bf16_f32 v8, v28, v29
	v_cvt_pk_bf16_f32 v9, v36, v37
	v_readlane_b32 s1, v248, 0
	v_cvt_pk_bf16_f32 v6, v16, v17
	v_cvt_pk_bf16_f32 v7, v26, v27
	v_cvt_pk_bf16_f32 v10, v24, v25
	v_cvt_pk_bf16_f32 v11, v30, v31
	ds_write2_b64 v2, v[4:5], v[8:9] offset0:4 offset1:6
	ds_write2_b64 v2, v[6:7], v[10:11] offset0:12 offset1:14
	s_lshl_b64 s[0:1], s[0:1], 1
	v_readlane_b32 s93, v249, 54
	s_waitcnt lgkmcnt(0)
	s_add_u32 s0, s93, s0
	v_readlane_b32 s94, v249, 55
	v_add3_u32 v14, s2, v163, v164
	s_addc_u32 s1, s94, s1
	v_readlane_b32 s3, v249, 62
	ds_read_b128 v[4:7], v14
	ds_read_b128 v[8:11], v14 offset:1152
	s_add_u32 s0, s0, s3
	s_addc_u32 s1, s1, 0
	v_lshlrev_b32_e32 v2, 1, v138
	v_lshl_add_u64 v[16:17], s[0:1], 0, v[2:3]
	v_lshl_add_u64 v[12:13], v[140:141], 1, v[16:17]
	s_waitcnt lgkmcnt(1)
	global_store_dwordx4 v[12:13], v[4:7], off
	ds_read_b128 v[4:7], v14 offset:2304
	ds_read_b128 v[12:15], v14 offset:3456
	v_lshl_add_u64 v[18:19], v[142:143], 1, v[16:17]
	s_waitcnt lgkmcnt(2)
	global_store_dwordx4 v[18:19], v[8:11], off
	v_readlane_b32 s88, v249, 56
	v_readlane_b32 s95, v249, 57
	v_lshl_add_u64 v[8:9], v[144:145], 1, v[16:17]
	s_waitcnt lgkmcnt(1)
	global_store_dwordx4 v[8:9], v[4:7], off
	v_readlane_b32 s96, v249, 58
	v_readlane_b32 s97, v249, 59
	v_lshl_add_u64 v[4:5], v[146:147], 1, v[16:17]
	s_waitcnt lgkmcnt(0)
	global_store_dwordx4 v[4:5], v[12:15], off
	s_waitcnt vmcnt(0) lgkmcnt(0)
	s_barrier

; __device__ __forceinline__ unsigned xb_add(unsigned* p, unsigned v) { return __hip_atomic_fetch_add(p, v, __ATOMIC_RELAXED, __HIP_MEMORY_SCOPE_AGENT); }
; __device__ __forceinline__ void xcd_barrier(const XcdBarrier& b) {
;     asm volatile("s_waitcnt vmcnt(0)" ::: "memory");
;     __syncthreads();
;     if (threadIdx.x == 0) {
;         unsigned* bar = b.bar;
;         __builtin_amdgcn_s_waitcnt(0);
;         unsigned nloc = b.st[0], nx = b.st[1];
;         if (nloc == 0u) { xcd_barrier_complete(bar, b.x, nloc, nx); b.st[0] = nloc; b.st[1] = nx; }
;         const unsigned old = xb_add(&bar[XB_XSUB(b.x)], 1u);
; __global__ void __launch_bounds__(NWAVES * 64, 2) fwd_megakernel(Args args) {
;     ...
;     xcd_barrier(xbar);
.LBB0_439:
	s_setprio 0
	s_waitcnt vmcnt(0)
	s_barrier
	s_mov_b64 s[0:1], exec
	v_readlane_b32 s84, v249, 0
	v_readlane_b32 s2, v249, 10
	v_readlane_b32 s66, v249, 37
	v_readlane_b32 s85, v249, 1
	v_readlane_b32 s90, v249, 6
	v_readlane_b32 s91, v249, 7
	v_readlane_b32 s3, v249, 11
	v_readlane_b32 s64, v249, 39
	v_readlane_b32 s67, v249, 38
	v_readlane_b32 s76, v249, 31
	v_readlane_b32 s70, v249, 43
	v_readlane_b32 s74, v249, 29
	v_readlane_b32 s84, v249, 14
	v_readlane_b32 s90, v249, 23
	s_and_b64 s[2:3], s[0:1], s[2:3]
	v_readlane_b32 s65, v249, 40
	v_readlane_b32 s68, v249, 35
	v_readlane_b32 s77, v249, 32
	v_readlane_b32 s78, v249, 33
	v_readlane_b32 s79, v249, 34
	v_readlane_b32 s71, v249, 44
	v_readlane_b32 s75, v249, 30
	v_readlane_b32 s63, v249, 28
	v_readlane_b32 s67, v249, 27
	v_readlane_b32 s80, v249, 8
	v_readlane_b32 s86, v249, 2
	v_readlane_b32 s87, v249, 3
	v_readlane_b32 s88, v249, 4
	v_readlane_b32 s89, v249, 5
	v_readlane_b32 s85, v249, 15
	v_readlane_b32 s91, v249, 24
	v_readlane_b32 s69, v249, 36
	v_readlane_b32 s81, v249, 9
	s_mov_b64 exec, s[2:3]
	s_cbranch_execz .LBB0_491
	s_add_i32 s2, 0, 0x23ff0
	v_mov_b32_e32 v2, s2
	s_waitcnt vmcnt(0) expcnt(0) lgkmcnt(0)
	ds_read_b32 v4, v2
	s_add_i32 s2, 0, 0x23ff4
	v_mov_b32_e32 v2, s2
	ds_read_b32 v2, v2
	s_waitcnt lgkmcnt(1)
	v_cmp_ne_u32_e32 vcc, 0, v4
	s_cbranch_vccnz .LBB0_455
	s_add_u32 s4, s70, 0x40200
	s_addc_u32 s5, s71, 0
	s_add_u32 s6, s70, 0x40400
	s_addc_u32 s7, s71, 0
	s_add_u32 s8, s70, 0x40500
	s_addc_u32 s9, s71, 0
	s_add_u32 s10, s70, 0x40600
	s_addc_u32 s11, s71, 0
	s_add_u32 s12, s70, 0x40700
	s_addc_u32 s13, s71, 0
	s_add_u32 s14, s70, 0x40800
	s_addc_u32 s15, s71, 0
	s_add_u32 s16, s70, 0x40900
	s_addc_u32 s17, s71, 0
	s_add_u32 s18, s70, 0x40a00
	s_addc_u32 s19, s71, 0
	s_add_u32 s20, s70, 0x40b00
	s_addc_u32 s21, s71, 0
	s_add_u32 s22, s70, 0x40c00
	s_addc_u32 s23, s71, 0
	s_add_u32 s24, s70, 0x40d00
	s_addc_u32 s25, s71, 0
	s_add_u32 s26, s70, 0x40e00
	s_addc_u32 s27, s71, 0
	s_add_u32 s28, s70, 0x40f00
	s_addc_u32 s29, s71, 0
	s_add_u32 s30, s70, 0x41000
	s_load_dwordx2 s[2:3], s[64:65], 0x4
	s_addc_u32 s31, s71, 0
	s_add_u32 s34, s70, 0x41100
	s_addc_u32 s35, s71, 0
	s_add_u32 s36, s70, 0x41200
	s_addc_u32 s37, s71, 0
	s_waitcnt lgkmcnt(0)
	s_mul_i32 s2, s2, s67
	s_add_u32 s38, s70, 0x41300
	s_mul_i32 s2, s2, s3
	s_addc_u32 s39, s71, 0
	s_mov_b32 s3, 1
	v_mov_b32_e32 v18, 0
	s_branch .LBB0_443
